# static priority mirrored: one s_setprio 1 for waves 0-3 at kernel entry, per-segment flips removed
# speedup vs baseline: 1.0128x; 1.0128x over previous
; #define LAS __attribute__((address_space(3)))
; __global__ void __launch_bounds__(512, 2) fwd_megakernel(Args a) {
;     extern __shared__ __attribute__((aligned(16))) unsigned char lds_raw[];
;     LAS unsigned char* lds = (LAS unsigned char*)lds_raw;
;     cg::grid_group grid = cg::this_grid();
;     const int wave_s = __builtin_amdgcn_readfirstlane((int)threadIdx.x >> 6);
;     ...
;     const int G = gridDim.x, bx = blockIdx.x, NGW = G * 8;
_Z14fwd_megakernel4Args:
	v_mov_b32_e32 v1, 0
	global_load_dword v1, v1, s[0:1] offset:206
	s_load_dwordx16 s[44:59], s[0:1], 0x80
	s_load_dword s60, s[0:1], 0xc8
	s_load_dwordx2 s[8:9], s[0:1], 0xc0
	v_and_b32_e32 v34, 0x3ff, v0
	s_add_u32 s6, s0, 0xc0
	v_readfirstlane_b32 s14, v34
	s_waitcnt lgkmcnt(0)
	s_mov_b64 s[4:5], s[58:59]
	s_mov_b32 s92, s2
	s_addc_u32 s7, s1, 0
	s_and_b32 s2, s14, 0xffffffc0
	s_cmp_lt_u32 s2, 0x100
	s_cbranch_scc0 .Lprio_done
	s_setprio 1
